# v52 with the w_in transpose issuing its loads in two batches of 16 instead of one of 32
# baseline (speedup 1.0000x reference)
.LBB0_118:
	s_lshl_b32 s4, s18, 6
	v_or_b32_e32 v5, s4, v62
	v_lshlrev_b64 v[48:49], 2, v[6:7]
	v_mad_i64_i32 v[34:35], s[18:19], v5, s67, v[48:49]
	v_or_b32_e32 v5, s4, v63
	v_mad_i64_i32 v[36:37], s[18:19], v5, s67, v[48:49]
	v_or_b32_e32 v5, s4, v64
	v_mad_i64_i32 v[38:39], s[18:19], v5, s67, v[48:49]
	v_or_b32_e32 v5, s4, v65
	v_mad_i64_i32 v[40:41], s[18:19], v5, s67, v[48:49]
	v_or_b32_e32 v5, s4, v66
	v_mad_i64_i32 v[42:43], s[18:19], v5, s67, v[48:49]
	v_or_b32_e32 v5, s4, v67
	v_mad_i64_i32 v[44:45], s[18:19], v5, s67, v[48:49]
	v_or_b32_e32 v5, s4, v68
	v_mad_i64_i32 v[46:47], s[18:19], v5, s67, v[48:49]
	v_or_b32_e32 v5, s4, v2
	v_mad_i64_i32 v[48:49], s[18:19], v5, s67, v[48:49]
	v_cmp_lt_i32_e32 vcc, -1, v6
	v_lshl_add_u64 v[34:35], s[24:25], 0, v[34:35]
	v_lshl_add_u64 v[36:37], s[24:25], 0, v[36:37]
	v_lshl_add_u64 v[38:39], s[24:25], 0, v[38:39]
	v_lshl_add_u64 v[40:41], s[24:25], 0, v[40:41]
	v_lshl_add_u64 v[42:43], s[24:25], 0, v[42:43]
	v_lshl_add_u64 v[44:45], s[24:25], 0, v[44:45]
	v_lshl_add_u64 v[46:47], s[24:25], 0, v[46:47]
	v_lshl_add_u64 v[48:49], s[24:25], 0, v[48:49]
	s_mov_b64 s[18:19], 0
	v_mov_b32_e32 v5, v61
	v_mov_b32_e32 v100, 0
	v_mov_b32_e32 v101, 0
	v_mov_b32_e32 v102, 0
	v_mov_b32_e32 v103, 0
	v_mov_b32_e32 v104, 0
	v_mov_b32_e32 v105, 0
	v_mov_b32_e32 v106, 0
	v_mov_b32_e32 v107, 0
	v_mov_b32_e32 v108, 0
	v_mov_b32_e32 v109, 0
	v_mov_b32_e32 v110, 0
	v_mov_b32_e32 v111, 0
	v_mov_b32_e32 v112, 0
	v_mov_b32_e32 v113, 0
	v_mov_b32_e32 v114, 0
	v_mov_b32_e32 v115, 0
	s_and_saveexec_b64 s[56:57], vcc
	global_load_dword v100, v[48:49], off
	global_load_dword v101, v[46:47], off
	global_load_dword v102, v[44:45], off
	global_load_dword v103, v[42:43], off
	global_load_dword v104, v[40:41], off
	global_load_dword v105, v[38:39], off
	global_load_dword v106, v[36:37], off
	global_load_dword v107, v[34:35], off
	s_mov_b32 s18, 0xc9000
	s_mov_b32 s19, 0
	v_lshl_add_u64 v[50:51], v[48:49], 0, s[18:19]
	global_load_dword v108, v[50:51], off
	v_lshl_add_u64 v[50:51], v[46:47], 0, s[18:19]
	global_load_dword v109, v[50:51], off
	v_lshl_add_u64 v[50:51], v[44:45], 0, s[18:19]
	global_load_dword v110, v[50:51], off
	v_lshl_add_u64 v[50:51], v[42:43], 0, s[18:19]
	global_load_dword v111, v[50:51], off
	v_lshl_add_u64 v[50:51], v[40:41], 0, s[18:19]
	global_load_dword v112, v[50:51], off
	v_lshl_add_u64 v[50:51], v[38:39], 0, s[18:19]
	global_load_dword v113, v[50:51], off
	v_lshl_add_u64 v[50:51], v[36:37], 0, s[18:19]
	global_load_dword v114, v[50:51], off
	v_lshl_add_u64 v[50:51], v[34:35], 0, s[18:19]
	global_load_dword v115, v[50:51], off
	s_or_b64 exec, exec, s[56:57]
	s_waitcnt vmcnt(8)
	ds_write_b32 v5, v100
	ds_write_b32 v5, v101 offset:264
	ds_write_b32 v5, v102 offset:528
	ds_write_b32 v5, v103 offset:792
	ds_write_b32 v5, v104 offset:1056
	ds_write_b32 v5, v105 offset:1320
	ds_write_b32 v5, v106 offset:1584
	ds_write_b32 v5, v107 offset:1848
	s_waitcnt vmcnt(0)
	ds_write_b32 v5, v108 offset:2112
	ds_write_b32 v5, v109 offset:2376
	ds_write_b32 v5, v110 offset:2640
	ds_write_b32 v5, v111 offset:2904
	ds_write_b32 v5, v112 offset:3168
	ds_write_b32 v5, v113 offset:3432
	ds_write_b32 v5, v114 offset:3696
	ds_write_b32 v5, v115 offset:3960
	v_mov_b32_e32 v116, 0
	v_mov_b32_e32 v117, 0
	v_mov_b32_e32 v118, 0
	v_mov_b32_e32 v119, 0
	v_mov_b32_e32 v120, 0
	v_mov_b32_e32 v121, 0
	v_mov_b32_e32 v122, 0
	v_mov_b32_e32 v123, 0
	v_mov_b32_e32 v124, 0
	v_mov_b32_e32 v125, 0
	v_mov_b32_e32 v126, 0
	v_mov_b32_e32 v127, 0
	v_mov_b32_e32 v128, 0
	v_mov_b32_e32 v129, 0
	v_mov_b32_e32 v130, 0
	v_mov_b32_e32 v131, 0
	s_and_saveexec_b64 s[56:57], vcc
	s_mov_b32 s18, 0x192000
	s_mov_b32 s19, 0
	v_lshl_add_u64 v[50:51], v[48:49], 0, s[18:19]
	global_load_dword v116, v[50:51], off
	v_lshl_add_u64 v[50:51], v[46:47], 0, s[18:19]
	global_load_dword v117, v[50:51], off
	v_lshl_add_u64 v[50:51], v[44:45], 0, s[18:19]
	global_load_dword v118, v[50:51], off
	v_lshl_add_u64 v[50:51], v[42:43], 0, s[18:19]
	global_load_dword v119, v[50:51], off
	v_lshl_add_u64 v[50:51], v[40:41], 0, s[18:19]
	global_load_dword v120, v[50:51], off
	v_lshl_add_u64 v[50:51], v[38:39], 0, s[18:19]
	global_load_dword v121, v[50:51], off
	v_lshl_add_u64 v[50:51], v[36:37], 0, s[18:19]
	global_load_dword v122, v[50:51], off
	v_lshl_add_u64 v[50:51], v[34:35], 0, s[18:19]
	global_load_dword v123, v[50:51], off
	s_mov_b32 s18, 0x25b000
	s_mov_b32 s19, 0
	v_lshl_add_u64 v[50:51], v[48:49], 0, s[18:19]
	global_load_dword v124, v[50:51], off
	v_lshl_add_u64 v[50:51], v[46:47], 0, s[18:19]
	global_load_dword v125, v[50:51], off
	v_lshl_add_u64 v[50:51], v[44:45], 0, s[18:19]
	global_load_dword v126, v[50:51], off
	v_lshl_add_u64 v[50:51], v[42:43], 0, s[18:19]
	global_load_dword v127, v[50:51], off
	v_lshl_add_u64 v[50:51], v[40:41], 0, s[18:19]
	global_load_dword v128, v[50:51], off
	v_lshl_add_u64 v[50:51], v[38:39], 0, s[18:19]
	global_load_dword v129, v[50:51], off
	v_lshl_add_u64 v[50:51], v[36:37], 0, s[18:19]
	global_load_dword v130, v[50:51], off
	v_lshl_add_u64 v[50:51], v[34:35], 0, s[18:19]
	global_load_dword v131, v[50:51], off
	s_or_b64 exec, exec, s[56:57]
	s_waitcnt vmcnt(8)
	ds_write_b32 v5, v116 offset:4224
	ds_write_b32 v5, v117 offset:4488
	ds_write_b32 v5, v118 offset:4752
	ds_write_b32 v5, v119 offset:5016
	ds_write_b32 v5, v120 offset:5280
	ds_write_b32 v5, v121 offset:5544
	ds_write_b32 v5, v122 offset:5808
	ds_write_b32 v5, v123 offset:6072
	s_waitcnt vmcnt(0)
	ds_write_b32 v5, v124 offset:6336
	ds_write_b32 v5, v125 offset:6600
	ds_write_b32 v5, v126 offset:6864
	ds_write_b32 v5, v127 offset:7128
	ds_write_b32 v5, v128 offset:7392
	ds_write_b32 v5, v129 offset:7656
	ds_write_b32 v5, v130 offset:7920
	ds_write_b32 v5, v131 offset:8184
	v_add_u32_e32 v5, 0x2100, v5
	s_mov_b32 s18, 0x324000
	s_mov_b32 s19, 0
	s_branch .LBB0_7
